# same as previous but 80 percent of layer 1-3 weight transposes deferred to the scan CU-mates (120 tiles per mate instead of 100)
# speedup vs baseline: 1.0006x; 1.0006x over previous
; __device__ __forceinline__ void phase_w(const Params p, char* smem) {
;     ...
;   for (int t = lbid(); t < L_ * PER_L; t += gridDim.x) {
;     int l = t / PER_L, r = t % PER_L;
;     if (r < 7392) {
;       transpose_tile<true>((const float*)p.in[I_WIN] + (size_t)l * D_ * NIN, NIN, (u16*)(ws + OFF_WIN) + (size_t)l * NINP * D_, D_,
;                      r / 231, r % 231, tile);
.LBB0_149:
	s_lshr_b32 s0, s73, 6
	s_cmp_eq_u32 s0, 4
	s_cbranch_scc0 .Lnot_mate
	v_readlane_b32 s0, v244, 43
	s_cmp_gt_u32 s0, 2
	s_cbranch_scc1 .LBB0_248
	s_add_i32 s0, s0, 1
	s_mul_i32 s20, s0, 0x2768
	s_add_i32 s101, s20, 7679
	s_add_i32 s20, s20, s73
	s_sub_i32 s20, s20, 0x100
	s_mov_b32 s100, 64
	s_branch .Ltramp_554

; __device__ __forceinline__ void phase_w(const Params p, char* smem) {
;     ...
;   for (int t = lbid(); t < L_ * PER_L; t += gridDim.x) {
;     int l = t / PER_L, r = t % PER_L;
.Lw_exit:
	s_cmp_eq_u32 s100, 64
	s_cbranch_scc1 .Lw_ret4
	s_cmp_eq_u32 s101, 0x9d9f
	s_cbranch_scc1 .LBB0_575
	s_add_i32 s20, s101, 7681
	s_add_i32 s101, s101, 0x2768
	s_add_i32 s20, s20, s73
	s_branch .LBB0_554
